# v008 + MFMA accumulator clear + P8 row scales (ssq) loaded one unit ahead into spare VGPRs
# speedup vs baseline: 1.0178x; 1.0000x over previous
.LBB0_157:
	s_ashr_i32 s37, s36, 31
	s_lshl_b64 s[34:35], s[36:37], 19
	s_add_u32 s38, s90, s34
	s_addc_u32 s39, s91, s35
	s_and_b64 s[34:35], s[2:3], exec
	s_cselect_b32 s5, s39, s29
	s_cselect_b32 s7, s38, s28
	s_ashr_i32 s27, s26, 31
	s_lshl_b64 s[34:35], s[26:27], 19
	s_add_u32 s40, s76, s34
	s_addc_u32 s41, s77, s35
	s_and_b64 s[34:35], s[2:3], exec
	s_cselect_b32 s27, s41, s31
	s_cselect_b32 s37, s40, s30
	s_add_u32 s28, s28, 0x40080
	s_addc_u32 s29, s29, 0
	s_add_u32 s63, s30, 0x100
	s_addc_u32 s64, s31, 0
	s_mov_b32 s65, -2
	v_mov_b32_e32 v252, 0
	v_mov_b32_e32 v253, 0
	v_mov_b32_e32 v254, 0
	v_mov_b32_e32 v255, 0
	s_nop 1
	v_mfma_f32_32x32x16_bf16 v[0:15], v[252:255], v[252:255], 0
	v_mfma_f32_32x32x16_bf16 v[16:31], v[252:255], v[252:255], 0
	v_mfma_f32_32x32x16_bf16 v[32:47], v[252:255], v[252:255], 0
	v_mfma_f32_32x32x16_bf16 v[48:63], v[252:255], v[252:255], 0
	v_mfma_f32_32x32x16_bf16 v[64:79], v[252:255], v[252:255], 0
	v_mfma_f32_32x32x16_bf16 v[80:95], v[252:255], v[252:255], 0
	v_mfma_f32_32x32x16_bf16 v[96:111], v[252:255], v[252:255], 0
	v_mfma_f32_32x32x16_bf16 v[112:127], v[252:255], v[252:255], 0

.LBB0_273:
	s_ashr_i32 s21, s20, 31
	s_lshl_b64 s[22:23], s[20:21], 18
	s_add_u32 s22, s35, s22
	s_addc_u32 s23, s36, s23
	s_and_b64 s[26:27], s[2:3], exec
	s_cselect_b32 s21, s23, s29
	s_cselect_b32 s54, s22, s28
	s_ashr_i32 s19, s18, 31
	s_lshl_b64 s[26:27], s[18:19], 19
	s_add_u32 s26, s74, s26
	s_addc_u32 s27, s75, s27
	s_and_b64 s[56:57], s[2:3], exec
	s_cselect_b32 s19, s27, s31
	s_cselect_b32 s55, s26, s30
	s_add_u32 s28, s28, 0x80
	s_addc_u32 s29, s29, 0
	s_add_u32 s56, s30, 0x100
	s_addc_u32 s57, s31, 0
	s_mov_b32 s58, -2
	v_mov_b32_e32 v252, 0
	v_mov_b32_e32 v253, 0
	v_mov_b32_e32 v254, 0
	v_mov_b32_e32 v255, 0
	s_nop 1
	v_mfma_f32_32x32x16_bf16 v[0:15], v[252:255], v[252:255], 0
	v_mfma_f32_32x32x16_bf16 v[16:31], v[252:255], v[252:255], 0
	v_mfma_f32_32x32x16_bf16 v[32:47], v[252:255], v[252:255], 0
	v_mfma_f32_32x32x16_bf16 v[48:63], v[252:255], v[252:255], 0

.LBB0_474:
	s_lshl_b32 s17, s44, 10
	s_ashr_i32 s19, s18, 31
	s_and_b32 s30, s17, 0x400
	s_lshl_b64 s[20:21], s[18:19], 19
	s_add_u32 s17, s90, s20
	s_addc_u32 s19, s91, s21
	s_add_u32 s20, s17, s30
	s_addc_u32 s21, s19, 0
	s_and_b64 s[22:23], s[2:3], exec
	s_cselect_b32 s19, s21, s27
	s_cselect_b32 s52, s20, s26
	s_ashr_i32 s17, s16, 31
	s_lshl_b64 s[22:23], s[16:17], 19
	s_add_u32 s17, s60, s22
	s_addc_u32 s23, s61, s23
	s_add_u32 s22, s17, s30
	s_addc_u32 s23, s23, 0
	s_and_b64 s[30:31], s[2:3], exec
	s_cselect_b32 s17, s23, s29
	s_cselect_b32 s53, s22, s28
	s_add_u32 s26, s26, 0x40080
	s_addc_u32 s27, s27, 0
	s_add_u32 s54, s28, 0x100
	s_addc_u32 s55, s29, 0
	s_mov_b32 s56, -2
	v_mov_b32_e32 v252, 0
	v_mov_b32_e32 v253, 0
	v_mov_b32_e32 v254, 0
	v_mov_b32_e32 v255, 0
	s_nop 1
	v_mfma_f32_32x32x16_bf16 v[0:15], v[252:255], v[252:255], 0
	v_mfma_f32_32x32x16_bf16 v[16:31], v[252:255], v[252:255], 0
	v_mfma_f32_32x32x16_bf16 v[32:47], v[252:255], v[252:255], 0
	v_mfma_f32_32x32x16_bf16 v[48:63], v[252:255], v[252:255], 0
	v_mfma_f32_32x32x16_bf16 v[64:79], v[252:255], v[252:255], 0
	v_mfma_f32_32x32x16_bf16 v[80:95], v[252:255], v[252:255], 0
	v_mfma_f32_32x32x16_bf16 v[96:111], v[252:255], v[252:255], 0
	v_mfma_f32_32x32x16_bf16 v[112:127], v[252:255], v[252:255], 0

.LBB0_508:
	s_add_i32 s54, s54, 1
	s_mul_i32 s26, s54, s86
	s_add_i32 s26, s26, s33
	s_mov_b32 s28, s65
	s_mov_b32 s29, s64
	s_and_b32 s64, s26, 3
	s_ashr_i32 s65, s26, 2
	s_cmpk_lt_i32 s26, 0x100
	s_cselect_b64 s[30:31], -1, 0
	s_and_b64 s[26:27], s[30:31], exec
	s_cselect_b32 s26, s64, s29
	s_cselect_b32 s38, s65, s28
	s_lshl_b32 s26, s26, 8
	s_lshl_b32 s28, s38, 19
	s_ashr_i32 s27, s26, 31
	s_and_b32 s28, s28, 0x180000
	s_add_u32 s39, s76, s28
	s_addc_u32 s66, s77, 0
	s_lshl_b64 s[28:29], s[26:27], 1
	s_add_u32 s26, s39, s28
	s_addc_u32 s27, s66, s29
	s_ashr_i32 s38, s38, 2
	s_ashr_i32 s39, s38, 31
	s_lshl_b64 s[38:39], s[38:39], 20
	s_add_u32 s38, s0, s38
	s_addc_u32 s39, s1, s39
	s_add_u32 s28, s38, s28
	s_addc_u32 s29, s39, s29
	s_add_u32 s28, s28, 0x800
	v_mov_b32_e32 v127, 0
	s_addc_u32 s29, s29, 0
	s_and_b64 vcc, exec, s[2:3]
	v_mov_b32_e32 v126, v127
	v_mov_b32_e32 v125, v127
	v_mov_b32_e32 v124, v127
	v_mov_b32_e32 v123, v127
	v_mov_b32_e32 v122, v127
	v_mov_b32_e32 v121, v127
	v_mov_b32_e32 v120, v127
	v_mov_b32_e32 v111, v127
	v_mov_b32_e32 v110, v127
	v_mov_b32_e32 v109, v127
	v_mov_b32_e32 v108, v127
	v_mov_b32_e32 v107, v127
	v_mov_b32_e32 v106, v127
	v_mov_b32_e32 v105, v127
	v_mov_b32_e32 v104, v127
	v_mov_b32_e32 v95, v127
	v_mov_b32_e32 v94, v127
	v_mov_b32_e32 v93, v127
	v_mov_b32_e32 v92, v127
	v_mov_b32_e32 v91, v127
	v_mov_b32_e32 v90, v127
	v_mov_b32_e32 v89, v127
	v_mov_b32_e32 v88, v127
	v_mov_b32_e32 v79, v127
	v_mov_b32_e32 v78, v127
	v_mov_b32_e32 v77, v127
	v_mov_b32_e32 v76, v127
	v_mov_b32_e32 v75, v127
	v_mov_b32_e32 v74, v127
	v_mov_b32_e32 v73, v127
	v_mov_b32_e32 v72, v127
	v_mov_b32_e32 v119, v127
	v_mov_b32_e32 v118, v127
	v_mov_b32_e32 v117, v127
	v_mov_b32_e32 v116, v127
	v_mov_b32_e32 v115, v127
	v_mov_b32_e32 v114, v127
	v_mov_b32_e32 v113, v127
	v_mov_b32_e32 v112, v127
	v_mov_b32_e32 v103, v127
	v_mov_b32_e32 v102, v127
	v_mov_b32_e32 v101, v127
	v_mov_b32_e32 v100, v127
	v_mov_b32_e32 v99, v127
	v_mov_b32_e32 v98, v127
	v_mov_b32_e32 v97, v127
	v_mov_b32_e32 v96, v127
	v_mov_b32_e32 v87, v127
	v_mov_b32_e32 v86, v127
	v_mov_b32_e32 v85, v127
	v_mov_b32_e32 v84, v127
	v_mov_b32_e32 v83, v127
	v_mov_b32_e32 v82, v127
	v_mov_b32_e32 v81, v127
	v_mov_b32_e32 v80, v127
	v_mov_b32_e32 v71, v127
	v_mov_b32_e32 v70, v127
	v_mov_b32_e32 v69, v127
	v_mov_b32_e32 v68, v127
	v_mov_b32_e32 v67, v127
	v_mov_b32_e32 v66, v127
	v_mov_b32_e32 v65, v127
	v_mov_b32_e32 v64, v127
	v_mov_b32_e32 v63, v127
	v_mov_b32_e32 v62, v127
	v_mov_b32_e32 v61, v127
	v_mov_b32_e32 v60, v127
	v_mov_b32_e32 v59, v127
	v_mov_b32_e32 v58, v127
	v_mov_b32_e32 v57, v127
	v_mov_b32_e32 v56, v127
	v_mov_b32_e32 v47, v127
	v_mov_b32_e32 v46, v127
	v_mov_b32_e32 v45, v127
	v_mov_b32_e32 v44, v127
	v_mov_b32_e32 v43, v127
	v_mov_b32_e32 v42, v127
	v_mov_b32_e32 v41, v127
	v_mov_b32_e32 v40, v127
	v_mov_b32_e32 v31, v127
	v_mov_b32_e32 v30, v127
	v_mov_b32_e32 v29, v127
	v_mov_b32_e32 v28, v127
	v_mov_b32_e32 v27, v127
	v_mov_b32_e32 v26, v127
	v_mov_b32_e32 v25, v127
	v_mov_b32_e32 v24, v127
	v_mov_b32_e32 v15, v127
	v_mov_b32_e32 v14, v127
	v_mov_b32_e32 v13, v127
	v_mov_b32_e32 v12, v127
	v_mov_b32_e32 v11, v127
	v_mov_b32_e32 v10, v127
	v_mov_b32_e32 v9, v127
	v_mov_b32_e32 v8, v127
	v_mov_b32_e32 v55, v127
	v_mov_b32_e32 v54, v127
	v_mov_b32_e32 v53, v127
	v_mov_b32_e32 v52, v127
	v_mov_b32_e32 v51, v127
	v_mov_b32_e32 v50, v127
	v_mov_b32_e32 v49, v127
	v_mov_b32_e32 v48, v127
	v_mov_b32_e32 v39, v127
	v_mov_b32_e32 v38, v127
	v_mov_b32_e32 v37, v127
	v_mov_b32_e32 v36, v127
	v_mov_b32_e32 v35, v127
	v_mov_b32_e32 v34, v127
	v_mov_b32_e32 v33, v127
	v_mov_b32_e32 v32, v127
	v_mov_b32_e32 v23, v127
	v_mov_b32_e32 v22, v127
	v_mov_b32_e32 v21, v127
	v_mov_b32_e32 v20, v127
	v_mov_b32_e32 v19, v127
	v_mov_b32_e32 v18, v127
	v_mov_b32_e32 v17, v127
	v_mov_b32_e32 v16, v127
	v_mov_b32_e32 v7, v127
	v_mov_b32_e32 v6, v127
	v_mov_b32_e32 v5, v127
	v_mov_b32_e32 v4, v127
	v_mov_b32_e32 v3, v127
	v_mov_b32_e32 v2, v127
	v_mov_b32_e32 v1, v127
	v_mov_b32_e32 v0, v127
	s_cbranch_vccnz .LBB0_511
	s_and_b64 s[38:39], s[30:31], exec
	s_cselect_b32 s66, s27, s35
	s_cselect_b32 s67, s26, s34
	s_cselect_b32 s68, s29, s37
	s_cselect_b32 s69, s28, s36
	s_add_u32 s34, s34, 0x40080
	s_addc_u32 s35, s35, 0
	s_add_u32 s70, s36, 0x100
	s_addc_u32 s71, s37, 0
	s_mov_b32 s36, 0
	v_mov_b32_e32 v252, 0
	v_mov_b32_e32 v253, 0
	v_mov_b32_e32 v254, 0
	v_mov_b32_e32 v255, 0
	s_nop 1
	v_mfma_f32_32x32x16_bf16 v[0:15], v[252:255], v[252:255], 0
	v_mfma_f32_32x32x16_bf16 v[16:31], v[252:255], v[252:255], 0
	v_mfma_f32_32x32x16_bf16 v[32:47], v[252:255], v[252:255], 0
	v_mfma_f32_32x32x16_bf16 v[48:63], v[252:255], v[252:255], 0
	v_mfma_f32_32x32x16_bf16 v[64:79], v[252:255], v[252:255], 0
	v_mfma_f32_32x32x16_bf16 v[80:95], v[252:255], v[252:255], 0
	v_mfma_f32_32x32x16_bf16 v[96:111], v[252:255], v[252:255], 0
	v_mfma_f32_32x32x16_bf16 v[112:127], v[252:255], v[252:255], 0

.LBB0_590:
	s_ashr_i32 s21, s20, 31
	s_lshl_b64 s[22:23], s[20:21], 19
	s_add_u32 s22, s10, s22
	s_addc_u32 s23, s11, s23
	s_and_b64 s[24:25], s[4:5], exec
	s_cselect_b32 s21, s23, s31
	s_cselect_b32 s27, s22, s30
	s_ashr_i32 s19, s18, 31
	s_lshl_b64 s[24:25], s[18:19], 19
	s_add_u32 s24, s62, s24
	s_addc_u32 s25, s63, s25
	s_and_b64 s[36:37], s[4:5], exec
	s_cselect_b32 s19, s25, s35
	s_cselect_b32 s55, s24, s34
	s_add_u32 s30, s30, 0x40080
	s_addc_u32 s31, s31, 0
	s_add_u32 s56, s34, 0x100
	s_addc_u32 s57, s35, 0
	s_mov_b32 s58, -2
	s_waitcnt lgkmcnt(0)
	v_mov_b32_e32 v252, 0
	v_mov_b32_e32 v253, 0
	v_mov_b32_e32 v254, 0
	v_mov_b32_e32 v255, 0
	s_nop 1
	v_mfma_f32_32x32x16_bf16 v[0:15], v[252:255], v[252:255], 0
	v_mfma_f32_32x32x16_bf16 v[16:31], v[252:255], v[252:255], 0
	v_mfma_f32_32x32x16_bf16 v[32:47], v[252:255], v[252:255], 0
	v_mfma_f32_32x32x16_bf16 v[48:63], v[252:255], v[252:255], 0
	v_mfma_f32_32x32x16_bf16 v[64:79], v[252:255], v[252:255], 0
	v_mfma_f32_32x32x16_bf16 v[80:95], v[252:255], v[252:255], 0
	v_mfma_f32_32x32x16_bf16 v[96:111], v[252:255], v[252:255], 0
	v_mfma_f32_32x32x16_bf16 v[112:127], v[252:255], v[252:255], 0

.LBB0_687:
	s_ashr_i32 s29, s28, 31
	s_lshl_b64 s[36:37], s[28:29], 19
	s_add_u32 s36, s8, s36
	s_addc_u32 s37, s9, s37
	s_and_b64 s[38:39], s[4:5], exec
	s_cselect_b32 s29, s37, s35
	s_cselect_b32 s31, s36, s34
	s_ashr_i32 s27, s26, 31
	s_lshl_b64 s[38:39], s[26:27], 19
	s_add_u32 s27, s52, s38
	s_addc_u32 s44, s53, s39
	s_ashr_i32 s38, s28, 3
	s_ashr_i32 s39, s38, 31
	s_lshl_b64 s[38:39], s[38:39], 21
	s_add_u32 s38, s27, s38
	s_addc_u32 s39, s44, s39
	s_and_b64 s[44:45], s[4:5], exec
	s_cselect_b32 s27, s39, s43
	s_cselect_b32 s70, s38, s42
	s_add_u32 s34, s34, 0x40080
	s_addc_u32 s35, s35, 0
	s_add_u32 s71, s42, 0x100
	s_addc_u32 s72, s43, 0
	s_mov_b32 s73, -2
	v_mov_b32_e32 v252, 0
	v_mov_b32_e32 v253, 0
	v_mov_b32_e32 v254, 0
	v_mov_b32_e32 v255, 0
	s_nop 1
	v_mfma_f32_32x32x16_bf16 v[0:15], v[252:255], v[252:255], 0
	v_mfma_f32_32x32x16_bf16 v[16:31], v[252:255], v[252:255], 0
	v_mfma_f32_32x32x16_bf16 v[32:47], v[252:255], v[252:255], 0
	v_mfma_f32_32x32x16_bf16 v[48:63], v[252:255], v[252:255], 0
	v_mfma_f32_32x32x16_bf16 v[64:79], v[252:255], v[252:255], 0
	v_mfma_f32_32x32x16_bf16 v[80:95], v[252:255], v[252:255], 0
	v_mfma_f32_32x32x16_bf16 v[96:111], v[252:255], v[252:255], 0
	v_mfma_f32_32x32x16_bf16 v[112:127], v[252:255], v[252:255], 0

.LBB0_802:
	s_ashr_i32 s27, s26, 31
	s_lshl_b64 s[30:31], s[26:27], 19
	s_add_u32 s30, s12, s30
	s_addc_u32 s31, s13, s31
	s_and_b64 s[0:1], s[0:1], exec
	s_cselect_b32 s25, s31, s41
	s_cselect_b32 s27, s30, s40
	s_add_u32 s0, s40, 0x40080
	s_addc_u32 s1, s41, 0
	s_add_u32 s60, s38, 0x100
	s_addc_u32 s61, s39, 0
	s_mov_b32 s62, -2
	s_waitcnt lgkmcnt(0)
	v_mov_b32_e32 v252, 0
	v_mov_b32_e32 v253, 0
	v_mov_b32_e32 v254, 0
	v_mov_b32_e32 v255, 0
	s_nop 1
	v_mfma_f32_32x32x16_bf16 v[0:15], v[252:255], v[252:255], 0
	v_mfma_f32_32x32x16_bf16 v[16:31], v[252:255], v[252:255], 0
	v_mfma_f32_32x32x16_bf16 v[32:47], v[252:255], v[252:255], 0
	v_mfma_f32_32x32x16_bf16 v[48:63], v[252:255], v[252:255], 0
	v_mfma_f32_32x32x16_bf16 v[64:79], v[252:255], v[252:255], 0
	v_mfma_f32_32x32x16_bf16 v[80:95], v[252:255], v[252:255], 0
	v_mfma_f32_32x32x16_bf16 v[96:111], v[252:255], v[252:255], 0
	v_mfma_f32_32x32x16_bf16 v[112:127], v[252:255], v[252:255], 0

.LBB0_884:
	s_add_u32 s12, s50, 0x140000
	s_addc_u32 s13, s51, 0
	s_lshl_b32 s14, s14, 5
	s_and_b32 s20, s14, 0x60
	s_mov_b64 s[14:15], 0x80
	s_add_i32 m0, s27, 0x18000
	v_lshl_add_u64 v[6:7], v[6:7], 0, s[14:15]
	s_ashr_i32 s43, s86, 31
	s_lshl_b32 s17, s16, 13
	s_lshl_b32 s21, s20, 7
	s_waitcnt vmcnt(2)
	s_barrier
	global_load_lds_dwordx4 v[6:7], off
	v_lshl_add_u64 v[4:5], v[4:5], 0, s[14:15]
	s_add_i32 m0, s27, 0x1a000
	s_add_i32 s44, s27, 0x8000
	s_add_i32 s45, s27, 0xa000
	global_load_lds_dwordx4 v[4:5], off
	v_lshl_add_u64 v[0:1], v[0:1], 0, s[14:15]
	s_mov_b32 m0, s44
	s_add_u32 s18, s30, 0x40080
	global_load_lds_dwordx4 v[0:1], off
	v_lshl_add_u64 v[0:1], v[2:3], 0, s[14:15]
	s_mov_b32 m0, s45
	s_addc_u32 s19, s31, 0
	global_load_lds_dwordx4 v[0:1], off
	s_add_i32 m0, s27, 0x1c000
	v_lshl_add_u64 v[0:1], s[18:19], 0, v[130:131]
	global_load_lds_dwordx4 v[0:1], off
	v_lshl_add_u64 v[0:1], s[18:19], 0, v[134:135]
	s_add_i32 m0, s27, 0x1e000
	s_sext_i32_i16 s55, s2
	global_load_lds_dwordx4 v[0:1], off
	v_and_b32_e32 v0, 15, v215
	v_lshlrev_b32_e32 v1, 1, v11
	v_lshlrev_b32_e32 v2, 6, v215
	s_movk_i32 s2, 0x3c0
	v_lshlrev_b32_e32 v3, 2, v215
	v_and_or_b32 v2, v2, s2, v1
	v_and_b32_e32 v3, 32, v3
	v_lshl_or_b32 v154, s16, 6, v0
	v_lshl_or_b32 v0, v0, 6, v1
	v_lshlrev_b32_e32 v1, 8, v215
	v_bitop3_b32 v155, s21, v2, v3 bitop3:0xf6
	v_and_b32_e32 v1, 0x38000, v1
	v_lshlrev_b32_e32 v2, 11, v10
	v_or3_b32 v1, v8, v1, v2
	v_add_u32_e32 v136, v1, v9
	v_lshlrev_b32_e32 v1, 4, v12
	s_waitcnt vmcnt(6)
	s_cmpk_lt_u32 s3, 0x100
	v_and_b32_e32 v1, 0x78000, v1
	v_bitop3_b32 v0, v0, s17, v3 bitop3:0xde
	s_cselect_b64 s[16:17], -1, 0
	v_or3_b32 v1, v8, v1, v2
	s_add_i32 s52, 0, 0x10000
	s_add_i32 s53, 0, 0x14000
	v_or_b32_e32 v156, s20, v11
	v_mov_b32_e32 v137, v131
	v_add_u32_e32 v138, v1, v9
	v_mov_b32_e32 v139, v131
	v_mov_b64_e32 v[140:141], 0xb00
	v_mov_b64_e32 v[142:143], 0xaff
	v_add_u32_e32 v157, s52, v155
	v_add_u32_e32 v158, s53, v155
	v_add_u32_e32 v159, 0, v0
	v_mov_b32_e32 v160, 0x358637bd
	s_movk_i32 s54, 0x1600
	s_barrier
	v_lshl_add_u32 v252, s26, 8, v154
	v_ashrrev_i32_e32 v253, 31, v252
	v_lshl_add_u64 v[252:253], v[252:253], 2, s[12:13]
	global_load_dword v244, v[252:253], off
	global_load_dword v245, v[252:253], off offset:64
	global_load_dword v246, v[252:253], off offset:128
	global_load_dword v247, v[252:253], off offset:192
	global_load_dword v248, v[252:253], off offset:512
	global_load_dword v249, v[252:253], off offset:576
	global_load_dword v250, v[252:253], off offset:640
	global_load_dword v251, v[252:253], off offset:704
	s_branch .LBB0_887

.LBB0_889:
	s_ashr_i32 s21, s20, 31
	s_lshl_b64 s[22:23], s[20:21], 19
	s_add_u32 s22, s6, s22
	s_addc_u32 s23, s7, s23
	s_and_b64 s[24:25], s[2:3], exec
	s_cselect_b32 s21, s23, s29
	s_cselect_b32 s56, s22, s28
	s_ashr_i32 s19, s18, 31
	s_lshl_b64 s[24:25], s[18:19], 19
	s_add_u32 s24, s82, s24
	s_addc_u32 s25, s83, s25
	s_and_b64 s[34:35], s[2:3], exec
	s_cselect_b32 s19, s25, s31
	s_cselect_b32 s57, s24, s30
	s_add_u32 s28, s28, 0x40080
	s_addc_u32 s29, s29, 0
	s_add_u32 s58, s30, 0x100
	s_addc_u32 s59, s31, 0
	s_mov_b32 s60, -2
	v_mov_b32_e32 v252, 0
	v_mov_b32_e32 v253, 0
	v_mov_b32_e32 v254, 0
	v_mov_b32_e32 v255, 0
	s_nop 1
	v_mfma_f32_32x32x16_bf16 v[0:15], v[252:255], v[252:255], 0
	v_mfma_f32_32x32x16_bf16 v[16:31], v[252:255], v[252:255], 0
	v_mfma_f32_32x32x16_bf16 v[32:47], v[252:255], v[252:255], 0
	v_mfma_f32_32x32x16_bf16 v[48:63], v[252:255], v[252:255], 0
	v_mfma_f32_32x32x16_bf16 v[64:79], v[252:255], v[252:255], 0
	v_mfma_f32_32x32x16_bf16 v[80:95], v[252:255], v[252:255], 0
	v_mfma_f32_32x32x16_bf16 v[96:111], v[252:255], v[252:255], 0
	v_mfma_f32_32x32x16_bf16 v[112:127], v[252:255], v[252:255], 0

.LBB0_893:
	v_lshl_add_u32 v146, s26, 8, v154
	v_or_b32_e32 v152, 16, v146
	v_or_b32_e32 v150, 32, v146
	v_ashrrev_i32_e32 v147, 31, v146
	v_ashrrev_i32_e32 v153, 31, v152
	v_ashrrev_i32_e32 v151, 31, v150
	v_or_b32_e32 v148, 48, v146
	v_lshl_add_u64 v[144:145], v[146:147], 2, s[12:13]
	v_lshl_add_u64 v[162:163], v[152:153], 2, s[12:13]
	v_lshl_add_u64 v[164:165], v[150:151], 2, s[12:13]
	v_ashrrev_i32_e32 v149, 31, v148
	v_lshl_add_u64 v[166:167], v[148:149], 2, s[12:13]
	s_nop 0
	v_mov_b32_e32 v168, v244
	v_mov_b32_e32 v178, v245
	v_mov_b32_e32 v179, v246
	v_mov_b32_e32 v180, v247
	v_mov_b32_e32 v164, v248
	v_mov_b32_e32 v162, v249
	v_mov_b32_e32 v153, v250
	v_mov_b32_e32 v149, v251
	v_lshl_or_b32 v147, s55, 8, v156
	v_mov_b64_e32 v[144:145], s[10:11]
	v_add_u32_e32 v165, 0x80, v146
	v_add_u32_e32 v163, 0x90, v146
	v_add_u32_e32 v161, 0xa0, v146
	v_add_u32_e32 v151, 0xb0, v146
	v_mad_i64_i32 v[166:167], s[28:29], v146, s54, v[144:145]
	v_ashrrev_i32_e32 v146, 1, v147
	v_ashrrev_i32_e32 v147, 31, v146
	v_lshlrev_b64 v[146:147], 1, v[146:147]
	v_lshl_add_u64 v[166:167], v[166:167], 0, v[146:147]
	s_andn2_b64 vcc, exec, s[2:3]
	s_mov_b64 s[2:3], -1
	s_nop 0
	v_fmamk_f32 v168, v168, 0x3a800000, v160
	v_rsq_f32_e32 v168, v168
	s_nop 0
	v_pk_mul_f32 v[126:127], v[126:127], v[168:169] op_sel_hi:[1,0]
	v_pk_mul_f32 v[124:125], v[124:125], v[168:169] op_sel_hi:[1,0]
	v_pk_mul_f32 v[122:123], v[122:123], v[168:169] op_sel_hi:[1,0]
	v_pk_mul_f32 v[120:121], v[120:121], v[168:169] op_sel_hi:[1,0]
	v_pk_mul_f32 v[118:119], v[118:119], v[168:169] op_sel_hi:[1,0]
	v_pk_mul_f32 v[116:117], v[116:117], v[168:169] op_sel_hi:[1,0]
	v_pk_mul_f32 v[114:115], v[114:115], v[168:169] op_sel_hi:[1,0]
	v_pk_mul_f32 v[112:113], v[112:113], v[168:169] op_sel_hi:[1,0]
	v_mul_f32_e32 v170, 0xbfb8aa3b, v124
	v_mul_f32_e32 v171, 0xbfb8aa3b, v126
	v_mul_f32_e32 v172, 0xbfb8aa3b, v120
	v_mul_f32_e32 v173, 0xbfb8aa3b, v122
	v_mul_f32_e32 v174, 0xbfb8aa3b, v116
	v_mul_f32_e32 v175, 0xbfb8aa3b, v118
	v_mul_f32_e32 v176, 0xbfb8aa3b, v112
	v_mul_f32_e32 v177, 0xbfb8aa3b, v114
	v_mov_b32_e32 v168, v124
	v_mov_b32_e32 v169, v126
	v_mov_b32_e32 v126, v125
	v_mov_b32_e32 v124, v120
	v_mov_b32_e32 v125, v122
	v_mov_b32_e32 v122, v121
	v_mov_b32_e32 v120, v116
	v_mov_b32_e32 v121, v118
	v_mov_b32_e32 v118, v117
	v_mov_b32_e32 v116, v112
	v_mov_b32_e32 v117, v114
	v_exp_f32_e32 v112, v170
	v_exp_f32_e32 v114, v171
	v_exp_f32_e32 v170, v172
	v_exp_f32_e32 v171, v173
	v_exp_f32_e32 v172, v174
	v_exp_f32_e32 v173, v175
	v_exp_f32_e32 v174, v176
	v_exp_f32_e32 v175, v177
	v_add_f32_e32 v176, 1.0, v170
	v_add_f32_e32 v177, 1.0, v171
	v_add_f32_e32 v183, 1.0, v174
	v_add_f32_e32 v184, 1.0, v175
	v_add_f32_e32 v181, 1.0, v172
	v_add_f32_e32 v182, 1.0, v173
	v_rcp_f32_e32 v172, v176
	v_rcp_f32_e32 v173, v177
	v_rcp_f32_e32 v176, v183
	v_rcp_f32_e32 v177, v184
	v_add_f32_e32 v114, 1.0, v114
	v_add_f32_e32 v112, 1.0, v112
	v_rcp_f32_e32 v171, v114
	v_pk_mul_f32 v[116:117], v[116:117], v[176:177]
	v_mov_b32_e32 v114, v113
	v_rcp_f32_e32 v170, v112
	v_pk_mul_f32 v[112:113], v[114:115], v[116:117]
	v_fmamk_f32 v114, v178, 0x3a800000, v160
	v_rcp_f32_e32 v174, v181
	v_rcp_f32_e32 v175, v182
	v_rsq_f32_e32 v114, v114
	v_cvt_pk_bf16_f32 v191, v112, v113
	v_pk_mul_f32 v[120:121], v[120:121], v[174:175]
	v_pk_mul_f32 v[110:111], v[110:111], v[114:115] op_sel_hi:[1,0]
	v_pk_mul_f32 v[108:109], v[108:109], v[114:115] op_sel_hi:[1,0]
	v_pk_mul_f32 v[118:119], v[118:119], v[120:121]
	v_mul_f32_e32 v112, 0xbfb8aa3b, v108
	v_mul_f32_e32 v113, 0xbfb8aa3b, v110
	v_cvt_pk_bf16_f32 v190, v118, v119
	v_exp_f32_e32 v112, v112
	v_exp_f32_e32 v113, v113
	v_pk_mul_f32 v[106:107], v[106:107], v[114:115] op_sel_hi:[1,0]
	v_pk_mul_f32 v[104:105], v[104:105], v[114:115] op_sel_hi:[1,0]
	v_mov_b32_e32 v116, v108
	v_mov_b32_e32 v117, v110
	v_mul_f32_e32 v108, 0xbfb8aa3b, v104
	v_mul_f32_e32 v110, 0xbfb8aa3b, v106
	v_exp_f32_e32 v108, v108
	v_exp_f32_e32 v115, v110
	v_add_f32_e32 v112, 1.0, v112
	v_add_f32_e32 v113, 1.0, v113
	v_rcp_f32_e32 v112, v112
	v_rcp_f32_e32 v113, v113
	v_mov_b32_e32 v110, v109
	v_add_f32_e32 v108, 1.0, v108
	v_add_f32_e32 v109, 1.0, v115
	v_rcp_f32_e32 v108, v108
	v_rcp_f32_e32 v109, v109
	v_pk_mul_f32 v[112:113], v[116:117], v[112:113]
	v_pk_mul_f32 v[102:103], v[102:103], v[114:115] op_sel_hi:[1,0]
	v_pk_mul_f32 v[110:111], v[110:111], v[112:113]
	v_mov_b32_e32 v112, v104
	v_mov_b32_e32 v113, v106
	v_pk_mul_f32 v[108:109], v[112:113], v[108:109]
	v_mov_b32_e32 v106, v105
	v_pk_mul_f32 v[104:105], v[106:107], v[108:109]
	v_cvt_pk_bf16_f32 v188, v110, v111
	v_cvt_pk_bf16_f32 v189, v104, v105
	v_mad_i64_i32 v[104:105], s[28:29], v152, s54, v[144:145]
	v_lshl_add_u64 v[104:105], v[104:105], 0, v[146:147]
	v_pk_mul_f32 v[100:101], v[100:101], v[114:115] op_sel_hi:[1,0]
	v_mul_f32_e32 v106, 0xbfb8aa3b, v100
	v_mul_f32_e32 v107, 0xbfb8aa3b, v102
	v_exp_f32_e32 v106, v106
	v_exp_f32_e32 v107, v107
	v_pk_mul_f32 v[98:99], v[98:99], v[114:115] op_sel_hi:[1,0]
	v_pk_mul_f32 v[96:97], v[96:97], v[114:115] op_sel_hi:[1,0]
	v_add_f32_e32 v106, 1.0, v106
	v_add_f32_e32 v107, 1.0, v107
	v_rcp_f32_e32 v106, v106
	v_rcp_f32_e32 v107, v107
	v_mov_b32_e32 v108, v100
	v_mov_b32_e32 v109, v102
	v_mul_f32_e32 v100, 0xbfb8aa3b, v96
	v_mul_f32_e32 v102, 0xbfb8aa3b, v98
	v_pk_mul_f32 v[106:107], v[108:109], v[106:107]
	v_exp_f32_e32 v100, v100
	v_exp_f32_e32 v108, v102
	v_mov_b32_e32 v102, v101
	v_pk_mul_f32 v[102:103], v[102:103], v[106:107]
	v_add_f32_e32 v100, 1.0, v100
	v_add_f32_e32 v101, 1.0, v108
	v_rcp_f32_e32 v100, v100
	v_rcp_f32_e32 v101, v101
	v_mov_b32_e32 v106, v96
	v_mov_b32_e32 v107, v98
	v_mov_b32_e32 v98, v97
	v_pk_mul_f32 v[100:101], v[106:107], v[100:101]
	v_pk_mul_f32 v[168:169], v[168:169], v[170:171]
	v_pk_mul_f32 v[96:97], v[98:99], v[100:101]
	v_fmamk_f32 v98, v179, 0x3a800000, v160
	v_rsq_f32_e32 v98, v98
	v_cvt_pk_bf16_f32 v193, v96, v97
	v_cvt_pk_bf16_f32 v192, v102, v103
	v_pk_mul_f32 v[94:95], v[94:95], v[98:99] op_sel_hi:[1,0]
	v_pk_mul_f32 v[92:93], v[92:93], v[98:99] op_sel_hi:[1,0]
	v_mul_f32_e32 v97, 0xbfb8aa3b, v94
	v_mul_f32_e32 v96, 0xbfb8aa3b, v92
	v_exp_f32_e32 v96, v96
	v_exp_f32_e32 v97, v97
	v_pk_mul_f32 v[90:91], v[90:91], v[98:99] op_sel_hi:[1,0]
	v_pk_mul_f32 v[88:89], v[88:89], v[98:99] op_sel_hi:[1,0]
	v_mov_b32_e32 v100, v92
	v_mov_b32_e32 v101, v94
	v_mul_f32_e32 v92, 0xbfb8aa3b, v88
	v_mul_f32_e32 v94, 0xbfb8aa3b, v90
	v_exp_f32_e32 v92, v92
	v_exp_f32_e32 v99, v94
	v_add_f32_e32 v96, 1.0, v96
	v_add_f32_e32 v97, 1.0, v97
	v_rcp_f32_e32 v96, v96
	v_rcp_f32_e32 v97, v97
	v_mov_b32_e32 v94, v93
	v_add_f32_e32 v92, 1.0, v92
	v_add_f32_e32 v93, 1.0, v99
	v_rcp_f32_e32 v92, v92
	v_rcp_f32_e32 v93, v93
	v_pk_mul_f32 v[96:97], v[100:101], v[96:97]
	v_pk_mul_f32 v[86:87], v[86:87], v[98:99] op_sel_hi:[1,0]
	v_pk_mul_f32 v[94:95], v[94:95], v[96:97]
	v_mov_b32_e32 v96, v88
	v_mov_b32_e32 v97, v90
	v_pk_mul_f32 v[92:93], v[96:97], v[92:93]
	v_mov_b32_e32 v90, v89
	v_pk_mul_f32 v[88:89], v[90:91], v[92:93]
	v_cvt_pk_bf16_f32 v194, v94, v95
	v_cvt_pk_bf16_f32 v195, v88, v89
	v_mad_i64_i32 v[88:89], s[28:29], v150, s54, v[144:145]
	v_lshl_add_u64 v[88:89], v[88:89], 0, v[146:147]
	v_pk_mul_f32 v[84:85], v[84:85], v[98:99] op_sel_hi:[1,0]
	v_mul_f32_e32 v90, 0xbfb8aa3b, v84
	v_mul_f32_e32 v91, 0xbfb8aa3b, v86
	v_exp_f32_e32 v90, v90
	v_exp_f32_e32 v91, v91
	v_pk_mul_f32 v[82:83], v[82:83], v[98:99] op_sel_hi:[1,0]
	v_pk_mul_f32 v[80:81], v[80:81], v[98:99] op_sel_hi:[1,0]
	v_add_f32_e32 v90, 1.0, v90
	v_add_f32_e32 v91, 1.0, v91
	v_rcp_f32_e32 v90, v90
	v_rcp_f32_e32 v91, v91
	v_mov_b32_e32 v92, v84
	v_mov_b32_e32 v93, v86
	v_mul_f32_e32 v84, 0xbfb8aa3b, v80
	v_mul_f32_e32 v86, 0xbfb8aa3b, v82
	v_pk_mul_f32 v[90:91], v[92:93], v[90:91]
	v_exp_f32_e32 v84, v84
	v_exp_f32_e32 v92, v86
	v_mov_b32_e32 v86, v85
	v_pk_mul_f32 v[86:87], v[86:87], v[90:91]
	v_add_f32_e32 v84, 1.0, v84
	v_add_f32_e32 v85, 1.0, v92
	v_rcp_f32_e32 v84, v84
	v_rcp_f32_e32 v85, v85
	v_mov_b32_e32 v90, v80
	v_mov_b32_e32 v91, v82
	v_mov_b32_e32 v82, v81
	v_pk_mul_f32 v[84:85], v[90:91], v[84:85]
	v_pk_mul_f32 v[124:125], v[124:125], v[172:173]
	v_pk_mul_f32 v[80:81], v[82:83], v[84:85]
	v_fmamk_f32 v82, v180, 0x3a800000, v160
	v_rsq_f32_e32 v82, v82
	v_cvt_pk_bf16_f32 v199, v80, v81
	v_cvt_pk_bf16_f32 v198, v86, v87
	v_pk_mul_f32 v[78:79], v[78:79], v[82:83] op_sel_hi:[1,0]
	v_pk_mul_f32 v[76:77], v[76:77], v[82:83] op_sel_hi:[1,0]
	v_mul_f32_e32 v81, 0xbfb8aa3b, v78
	v_mul_f32_e32 v80, 0xbfb8aa3b, v76
	v_exp_f32_e32 v80, v80
	v_exp_f32_e32 v81, v81
	v_pk_mul_f32 v[74:75], v[74:75], v[82:83] op_sel_hi:[1,0]
	v_pk_mul_f32 v[72:73], v[72:73], v[82:83] op_sel_hi:[1,0]
	v_mov_b32_e32 v84, v76
	v_mov_b32_e32 v85, v78
	v_mul_f32_e32 v76, 0xbfb8aa3b, v72
	v_mul_f32_e32 v78, 0xbfb8aa3b, v74
	v_exp_f32_e32 v76, v76
	v_exp_f32_e32 v83, v78
	v_add_f32_e32 v80, 1.0, v80
	v_add_f32_e32 v81, 1.0, v81
	v_rcp_f32_e32 v80, v80
	v_rcp_f32_e32 v81, v81
	v_mov_b32_e32 v78, v77
	v_add_f32_e32 v76, 1.0, v76
	v_add_f32_e32 v77, 1.0, v83
	v_rcp_f32_e32 v76, v76
	v_rcp_f32_e32 v77, v77
	v_pk_mul_f32 v[80:81], v[84:85], v[80:81]
	v_pk_mul_f32 v[70:71], v[70:71], v[82:83] op_sel_hi:[1,0]
	v_pk_mul_f32 v[78:79], v[78:79], v[80:81]
	v_mov_b32_e32 v80, v72
	v_mov_b32_e32 v81, v74
	v_pk_mul_f32 v[76:77], v[80:81], v[76:77]
	v_mov_b32_e32 v74, v73
	v_pk_mul_f32 v[72:73], v[74:75], v[76:77]
	v_cvt_pk_bf16_f32 v196, v78, v79
	v_cvt_pk_bf16_f32 v197, v72, v73
	v_mad_i64_i32 v[72:73], s[28:29], v148, s54, v[144:145]
	v_lshl_add_u64 v[72:73], v[72:73], 0, v[146:147]
	v_pk_mul_f32 v[68:69], v[68:69], v[82:83] op_sel_hi:[1,0]
	v_mul_f32_e32 v74, 0xbfb8aa3b, v68
	v_mul_f32_e32 v75, 0xbfb8aa3b, v70
	v_exp_f32_e32 v74, v74
	v_exp_f32_e32 v75, v75
	v_pk_mul_f32 v[66:67], v[66:67], v[82:83] op_sel_hi:[1,0]
	v_pk_mul_f32 v[64:65], v[64:65], v[82:83] op_sel_hi:[1,0]
	v_add_f32_e32 v74, 1.0, v74
	v_add_f32_e32 v75, 1.0, v75
	v_rcp_f32_e32 v74, v74
	v_rcp_f32_e32 v75, v75
	v_mov_b32_e32 v76, v68
	v_mov_b32_e32 v77, v70
	v_mul_f32_e32 v68, 0xbfb8aa3b, v64
	v_mul_f32_e32 v70, 0xbfb8aa3b, v66
	v_pk_mul_f32 v[74:75], v[76:77], v[74:75]
	v_exp_f32_e32 v68, v68
	v_exp_f32_e32 v76, v70
	v_mov_b32_e32 v70, v69
	v_pk_mul_f32 v[70:71], v[70:71], v[74:75]
	v_add_f32_e32 v68, 1.0, v68
	v_add_f32_e32 v69, 1.0, v76
	v_rcp_f32_e32 v68, v68
	v_rcp_f32_e32 v69, v69
	v_mov_b32_e32 v74, v64
	v_mov_b32_e32 v75, v66
	v_mov_b32_e32 v66, v65
	v_pk_mul_f32 v[68:69], v[74:75], v[68:69]
	v_pk_mul_f32 v[126:127], v[126:127], v[168:169]
	v_pk_mul_f32 v[64:65], v[66:67], v[68:69]
	v_fmamk_f32 v66, v164, 0x3a800000, v160
	v_rsq_f32_e32 v66, v66
	v_cvt_pk_bf16_f32 v201, v64, v65
	v_cvt_pk_bf16_f32 v200, v70, v71
	v_pk_mul_f32 v[62:63], v[62:63], v[66:67] op_sel_hi:[1,0]
	v_pk_mul_f32 v[60:61], v[60:61], v[66:67] op_sel_hi:[1,0]
	v_mul_f32_e32 v65, 0xbfb8aa3b, v62
	v_mul_f32_e32 v64, 0xbfb8aa3b, v60
	v_exp_f32_e32 v64, v64
	v_exp_f32_e32 v65, v65
	v_pk_mul_f32 v[58:59], v[58:59], v[66:67] op_sel_hi:[1,0]
	v_pk_mul_f32 v[56:57], v[56:57], v[66:67] op_sel_hi:[1,0]
	v_mov_b32_e32 v68, v60
	v_mov_b32_e32 v69, v62
	v_mul_f32_e32 v60, 0xbfb8aa3b, v56
	v_mul_f32_e32 v62, 0xbfb8aa3b, v58
	v_exp_f32_e32 v60, v60
	v_exp_f32_e32 v67, v62
	v_add_f32_e32 v64, 1.0, v64
	v_add_f32_e32 v65, 1.0, v65
	v_rcp_f32_e32 v64, v64
	v_rcp_f32_e32 v65, v65
	v_mov_b32_e32 v62, v61
	v_add_f32_e32 v60, 1.0, v60
	v_add_f32_e32 v61, 1.0, v67
	v_rcp_f32_e32 v60, v60
	v_rcp_f32_e32 v61, v61
	v_pk_mul_f32 v[64:65], v[68:69], v[64:65]
	v_pk_mul_f32 v[54:55], v[54:55], v[66:67] op_sel_hi:[1,0]
	v_pk_mul_f32 v[62:63], v[62:63], v[64:65]
	v_mov_b32_e32 v64, v56
	v_mov_b32_e32 v65, v58
	v_pk_mul_f32 v[60:61], v[64:65], v[60:61]
	v_mov_b32_e32 v58, v57
	v_pk_mul_f32 v[56:57], v[58:59], v[60:61]
	v_cvt_pk_bf16_f32 v202, v62, v63
	v_cvt_pk_bf16_f32 v203, v56, v57
	v_mad_i64_i32 v[56:57], s[28:29], v165, s54, v[144:145]
	v_lshl_add_u64 v[56:57], v[56:57], 0, v[146:147]
	v_pk_mul_f32 v[52:53], v[52:53], v[66:67] op_sel_hi:[1,0]
	v_mul_f32_e32 v58, 0xbfb8aa3b, v52
	v_mul_f32_e32 v59, 0xbfb8aa3b, v54
	v_exp_f32_e32 v58, v58
	v_exp_f32_e32 v59, v59
	v_pk_mul_f32 v[50:51], v[50:51], v[66:67] op_sel_hi:[1,0]
	v_pk_mul_f32 v[48:49], v[48:49], v[66:67] op_sel_hi:[1,0]
	v_add_f32_e32 v58, 1.0, v58
	v_add_f32_e32 v59, 1.0, v59
	v_rcp_f32_e32 v58, v58
	v_rcp_f32_e32 v59, v59
	v_mov_b32_e32 v60, v52
	v_mov_b32_e32 v61, v54
	v_mul_f32_e32 v52, 0xbfb8aa3b, v48
	v_mul_f32_e32 v54, 0xbfb8aa3b, v50
	v_pk_mul_f32 v[58:59], v[60:61], v[58:59]
	v_exp_f32_e32 v52, v52
	v_exp_f32_e32 v60, v54
	v_mov_b32_e32 v54, v53
	v_pk_mul_f32 v[54:55], v[54:55], v[58:59]
	v_add_f32_e32 v52, 1.0, v52
	v_add_f32_e32 v53, 1.0, v60
	v_rcp_f32_e32 v52, v52
	v_rcp_f32_e32 v53, v53
	v_mov_b32_e32 v58, v48
	v_mov_b32_e32 v59, v50
	v_mov_b32_e32 v50, v49
	v_pk_mul_f32 v[52:53], v[58:59], v[52:53]
	v_pk_mul_f32 v[122:123], v[122:123], v[124:125]
	v_pk_mul_f32 v[48:49], v[50:51], v[52:53]
	v_fmamk_f32 v50, v162, 0x3a800000, v160
	v_rsq_f32_e32 v50, v50
	v_cvt_pk_bf16_f32 v207, v48, v49
	v_cvt_pk_bf16_f32 v206, v54, v55
	v_pk_mul_f32 v[46:47], v[46:47], v[50:51] op_sel_hi:[1,0]
	v_pk_mul_f32 v[44:45], v[44:45], v[50:51] op_sel_hi:[1,0]
	v_mul_f32_e32 v49, 0xbfb8aa3b, v46
	v_mul_f32_e32 v48, 0xbfb8aa3b, v44
	v_exp_f32_e32 v48, v48
	v_exp_f32_e32 v49, v49
	v_pk_mul_f32 v[42:43], v[42:43], v[50:51] op_sel_hi:[1,0]
	v_pk_mul_f32 v[40:41], v[40:41], v[50:51] op_sel_hi:[1,0]
	v_mov_b32_e32 v52, v44
	v_mov_b32_e32 v53, v46
	v_mul_f32_e32 v44, 0xbfb8aa3b, v40
	v_mul_f32_e32 v46, 0xbfb8aa3b, v42
	v_exp_f32_e32 v44, v44
	v_exp_f32_e32 v51, v46
	v_add_f32_e32 v48, 1.0, v48
	v_add_f32_e32 v49, 1.0, v49
	v_rcp_f32_e32 v48, v48
	v_rcp_f32_e32 v49, v49
	v_mov_b32_e32 v46, v45
	v_add_f32_e32 v44, 1.0, v44
	v_add_f32_e32 v45, 1.0, v51
	v_rcp_f32_e32 v44, v44
	v_rcp_f32_e32 v45, v45
	v_pk_mul_f32 v[48:49], v[52:53], v[48:49]
	v_pk_mul_f32 v[38:39], v[38:39], v[50:51] op_sel_hi:[1,0]
	v_pk_mul_f32 v[46:47], v[46:47], v[48:49]
	v_mov_b32_e32 v48, v40
	v_mov_b32_e32 v49, v42
	v_pk_mul_f32 v[44:45], v[48:49], v[44:45]
	v_mov_b32_e32 v42, v41
	v_pk_mul_f32 v[40:41], v[42:43], v[44:45]
	v_cvt_pk_bf16_f32 v204, v46, v47
	v_cvt_pk_bf16_f32 v205, v40, v41
	v_mad_i64_i32 v[40:41], s[28:29], v163, s54, v[144:145]
	v_lshl_add_u64 v[40:41], v[40:41], 0, v[146:147]
	v_pk_mul_f32 v[36:37], v[36:37], v[50:51] op_sel_hi:[1,0]
	v_mul_f32_e32 v42, 0xbfb8aa3b, v36
	v_mul_f32_e32 v43, 0xbfb8aa3b, v38
	v_exp_f32_e32 v42, v42
	v_exp_f32_e32 v43, v43
	v_pk_mul_f32 v[34:35], v[34:35], v[50:51] op_sel_hi:[1,0]
	v_pk_mul_f32 v[32:33], v[32:33], v[50:51] op_sel_hi:[1,0]
	v_add_f32_e32 v42, 1.0, v42
	v_add_f32_e32 v43, 1.0, v43
	v_rcp_f32_e32 v42, v42
	v_rcp_f32_e32 v43, v43
	v_mov_b32_e32 v44, v36
	v_mov_b32_e32 v45, v38
	v_mul_f32_e32 v36, 0xbfb8aa3b, v32
	v_mul_f32_e32 v38, 0xbfb8aa3b, v34
	v_pk_mul_f32 v[42:43], v[44:45], v[42:43]
	v_exp_f32_e32 v36, v36
	v_exp_f32_e32 v44, v38
	v_mov_b32_e32 v38, v37
	v_pk_mul_f32 v[38:39], v[38:39], v[42:43]
	v_add_f32_e32 v36, 1.0, v36
	v_add_f32_e32 v37, 1.0, v44
	v_rcp_f32_e32 v36, v36
	v_rcp_f32_e32 v37, v37
	v_mov_b32_e32 v42, v32
	v_mov_b32_e32 v43, v34
	v_mov_b32_e32 v34, v33
	v_pk_mul_f32 v[36:37], v[42:43], v[36:37]
	v_cvt_pk_bf16_f32 v186, v126, v127
	v_pk_mul_f32 v[32:33], v[34:35], v[36:37]
	v_fmamk_f32 v34, v153, 0x3a800000, v160
	v_rsq_f32_e32 v34, v34
	v_cvt_pk_bf16_f32 v209, v32, v33
	v_cvt_pk_bf16_f32 v208, v38, v39
	v_pk_mul_f32 v[30:31], v[30:31], v[34:35] op_sel_hi:[1,0]
	v_pk_mul_f32 v[28:29], v[28:29], v[34:35] op_sel_hi:[1,0]
	v_mul_f32_e32 v33, 0xbfb8aa3b, v30
	v_mul_f32_e32 v32, 0xbfb8aa3b, v28
	v_exp_f32_e32 v32, v32
	v_exp_f32_e32 v33, v33
	v_pk_mul_f32 v[26:27], v[26:27], v[34:35] op_sel_hi:[1,0]
	v_pk_mul_f32 v[24:25], v[24:25], v[34:35] op_sel_hi:[1,0]
	v_mov_b32_e32 v36, v28
	v_mov_b32_e32 v37, v30
	v_mul_f32_e32 v28, 0xbfb8aa3b, v24
	v_mul_f32_e32 v30, 0xbfb8aa3b, v26
	v_exp_f32_e32 v28, v28
	v_exp_f32_e32 v35, v30
	v_add_f32_e32 v32, 1.0, v32
	v_add_f32_e32 v33, 1.0, v33
	v_rcp_f32_e32 v32, v32
	v_rcp_f32_e32 v33, v33
	v_mov_b32_e32 v30, v29
	v_add_f32_e32 v28, 1.0, v28
	v_add_f32_e32 v29, 1.0, v35
	v_rcp_f32_e32 v28, v28
	v_rcp_f32_e32 v29, v29
	v_pk_mul_f32 v[32:33], v[36:37], v[32:33]
	v_pk_mul_f32 v[22:23], v[22:23], v[34:35] op_sel_hi:[1,0]
	v_pk_mul_f32 v[30:31], v[30:31], v[32:33]
	v_mov_b32_e32 v32, v24
	v_mov_b32_e32 v33, v26
	v_pk_mul_f32 v[28:29], v[32:33], v[28:29]
	v_mov_b32_e32 v26, v25
	v_pk_mul_f32 v[24:25], v[26:27], v[28:29]
	v_cvt_pk_bf16_f32 v210, v30, v31
	v_cvt_pk_bf16_f32 v211, v24, v25
	v_mad_i64_i32 v[24:25], s[28:29], v161, s54, v[144:145]
	v_lshl_add_u64 v[24:25], v[24:25], 0, v[146:147]
	v_pk_mul_f32 v[20:21], v[20:21], v[34:35] op_sel_hi:[1,0]
	v_mul_f32_e32 v26, 0xbfb8aa3b, v20
	v_mul_f32_e32 v27, 0xbfb8aa3b, v22
	v_exp_f32_e32 v26, v26
	v_exp_f32_e32 v27, v27
	v_pk_mul_f32 v[18:19], v[18:19], v[34:35] op_sel_hi:[1,0]
	v_pk_mul_f32 v[16:17], v[16:17], v[34:35] op_sel_hi:[1,0]
	v_add_f32_e32 v26, 1.0, v26
	v_add_f32_e32 v27, 1.0, v27
	v_rcp_f32_e32 v26, v26
	v_rcp_f32_e32 v27, v27
	v_mov_b32_e32 v28, v20
	v_mov_b32_e32 v29, v22
	v_mul_f32_e32 v20, 0xbfb8aa3b, v16
	v_mul_f32_e32 v22, 0xbfb8aa3b, v18
	v_pk_mul_f32 v[26:27], v[28:29], v[26:27]
	v_exp_f32_e32 v20, v20
	v_exp_f32_e32 v28, v22
	v_mov_b32_e32 v22, v21
	v_pk_mul_f32 v[22:23], v[22:23], v[26:27]
	v_add_f32_e32 v20, 1.0, v20
	v_add_f32_e32 v21, 1.0, v28
	v_rcp_f32_e32 v20, v20
	v_rcp_f32_e32 v21, v21
	v_mov_b32_e32 v26, v16
	v_mov_b32_e32 v27, v18
	v_mov_b32_e32 v18, v17
	v_pk_mul_f32 v[20:21], v[26:27], v[20:21]
	v_cvt_pk_bf16_f32 v187, v122, v123
	v_pk_mul_f32 v[16:17], v[18:19], v[20:21]
	v_fmamk_f32 v18, v149, 0x3a800000, v160
	v_rsq_f32_e32 v18, v18
	v_cvt_pk_bf16_f32 v217, v16, v17
	v_cvt_pk_bf16_f32 v216, v22, v23
	v_pk_mul_f32 v[14:15], v[14:15], v[18:19] op_sel_hi:[1,0]
	v_pk_mul_f32 v[12:13], v[12:13], v[18:19] op_sel_hi:[1,0]
	v_mul_f32_e32 v17, 0xbfb8aa3b, v14
	v_mul_f32_e32 v16, 0xbfb8aa3b, v12
	v_exp_f32_e32 v16, v16
	v_exp_f32_e32 v17, v17
	v_pk_mul_f32 v[10:11], v[10:11], v[18:19] op_sel_hi:[1,0]
	v_pk_mul_f32 v[8:9], v[8:9], v[18:19] op_sel_hi:[1,0]
	v_mov_b32_e32 v20, v12
	v_mov_b32_e32 v21, v14
	v_mul_f32_e32 v12, 0xbfb8aa3b, v8
	v_mul_f32_e32 v14, 0xbfb8aa3b, v10
	v_exp_f32_e32 v12, v12
	v_exp_f32_e32 v19, v14
	v_add_f32_e32 v16, 1.0, v16
	v_add_f32_e32 v17, 1.0, v17
	v_rcp_f32_e32 v16, v16
	v_rcp_f32_e32 v17, v17
	v_mov_b32_e32 v14, v13
	v_add_f32_e32 v12, 1.0, v12
	v_add_f32_e32 v13, 1.0, v19
	v_rcp_f32_e32 v12, v12
	v_rcp_f32_e32 v13, v13
	v_pk_mul_f32 v[16:17], v[20:21], v[16:17]
	v_pk_mul_f32 v[6:7], v[6:7], v[18:19] op_sel_hi:[1,0]
	v_pk_mul_f32 v[14:15], v[14:15], v[16:17]
	v_mov_b32_e32 v16, v8
	v_mov_b32_e32 v17, v10
	v_pk_mul_f32 v[12:13], v[16:17], v[12:13]
	v_mov_b32_e32 v10, v9
	v_pk_mul_f32 v[8:9], v[10:11], v[12:13]
	v_cvt_pk_bf16_f32 v212, v14, v15
	v_cvt_pk_bf16_f32 v213, v8, v9
	v_mad_i64_i32 v[8:9], s[28:29], v151, s54, v[144:145]
	v_lshl_add_u64 v[8:9], v[8:9], 0, v[146:147]
	v_pk_mul_f32 v[4:5], v[4:5], v[18:19] op_sel_hi:[1,0]
	v_mul_f32_e32 v10, 0xbfb8aa3b, v4
	v_mul_f32_e32 v11, 0xbfb8aa3b, v6
	v_exp_f32_e32 v10, v10
	v_exp_f32_e32 v11, v11
	v_pk_mul_f32 v[2:3], v[2:3], v[18:19] op_sel_hi:[1,0]
	v_pk_mul_f32 v[0:1], v[0:1], v[18:19] op_sel_hi:[1,0]
	v_add_f32_e32 v10, 1.0, v10
	v_add_f32_e32 v11, 1.0, v11
	v_rcp_f32_e32 v10, v10
	v_rcp_f32_e32 v11, v11
	v_mov_b32_e32 v12, v4
	v_mov_b32_e32 v13, v6
	v_mul_f32_e32 v4, 0xbfb8aa3b, v0
	v_mul_f32_e32 v6, 0xbfb8aa3b, v2
	v_pk_mul_f32 v[10:11], v[12:13], v[10:11]
	v_exp_f32_e32 v4, v4
	v_exp_f32_e32 v12, v6
	v_mov_b32_e32 v6, v5
	v_pk_mul_f32 v[6:7], v[6:7], v[10:11]
	v_add_f32_e32 v4, 1.0, v4
	v_add_f32_e32 v5, 1.0, v12
	v_rcp_f32_e32 v4, v4
	v_rcp_f32_e32 v5, v5
	v_mov_b32_e32 v10, v0
	v_mov_b32_e32 v11, v2
	v_mov_b32_e32 v2, v1
	v_pk_mul_f32 v[4:5], v[10:11], v[4:5]
	v_pk_mul_f32 v[0:1], v[2:3], v[4:5]
	v_cvt_pk_bf16_f32 v218, v6, v7
	v_cvt_pk_bf16_f32 v219, v0, v1
	v_lshrrev_b32_e32 v162, 4, v214
	v_and_b32_e32 v162, 1, v162
	v_mul_u32_u24_e32 v162, 0x15ff8, v162
	v_mov_b32_e32 v163, 0
	v_lshl_add_u64 v[164:165], v[166:167], 0, v[162:163]
	s_mov_b64 s[64:65], 0x2c000
	s_mov_b64 s[66:67], 0x84000
	v_permlane16_swap_b32_e32 v186, v188
	v_permlane16_swap_b32_e32 v187, v189
	global_store_dwordx4 v[164:165], v[186:189], off
	v_permlane16_swap_b32_e32 v190, v192
	v_permlane16_swap_b32_e32 v191, v193
	global_store_dwordx4 v[164:165], v[190:193], off offset:128
	v_lshl_add_u64 v[164:165], v[164:165], 0, s[64:65]
	v_permlane16_swap_b32_e32 v194, v196
	v_permlane16_swap_b32_e32 v195, v197
	global_store_dwordx4 v[164:165], v[194:197], off
	v_permlane16_swap_b32_e32 v198, v200
	v_permlane16_swap_b32_e32 v199, v201
	global_store_dwordx4 v[164:165], v[198:201], off offset:128
	v_lshl_add_u64 v[164:165], v[164:165], 0, s[66:67]
	v_permlane16_swap_b32_e32 v202, v204
	v_permlane16_swap_b32_e32 v203, v205
	global_store_dwordx4 v[164:165], v[202:205], off
	v_permlane16_swap_b32_e32 v206, v208
	v_permlane16_swap_b32_e32 v207, v209
	global_store_dwordx4 v[164:165], v[206:209], off offset:128
	v_lshl_add_u64 v[164:165], v[164:165], 0, s[64:65]
	v_permlane16_swap_b32_e32 v210, v212
	v_permlane16_swap_b32_e32 v211, v213
	global_store_dwordx4 v[164:165], v[210:213], off
	v_permlane16_swap_b32_e32 v216, v218
	v_permlane16_swap_b32_e32 v217, v219
	global_store_dwordx4 v[164:165], v[216:219], off offset:128
	s_cbranch_vccnz .LBB0_886
	v_lshl_add_u32 v252, s20, 8, v154
	v_ashrrev_i32_e32 v253, 31, v252
	v_lshl_add_u64 v[252:253], v[252:253], 2, s[12:13]
	global_load_dword v244, v[252:253], off
	global_load_dword v245, v[252:253], off offset:64
	global_load_dword v246, v[252:253], off offset:128
	global_load_dword v247, v[252:253], off offset:192
	global_load_dword v248, v[252:253], off offset:512
	global_load_dword v249, v[252:253], off offset:576
	global_load_dword v250, v[252:253], off offset:640
	global_load_dword v251, v[252:253], off offset:704
	s_andn2_b64 vcc, exec, s[4:5]
	s_cbranch_vccnz .LBB0_885
	s_barrier
	s_branch .LBB0_885

.LBB0_974:
	s_add_u32 s24, s24, 0xb0080
	s_addc_u32 s25, s25, 0
	s_add_u32 s54, s26, 0x100
	s_addc_u32 s55, s27, 0
	s_mov_b32 s56, -2
	s_waitcnt lgkmcnt(0)
	v_mov_b32_e32 v252, 0
	v_mov_b32_e32 v253, 0
	v_mov_b32_e32 v254, 0
	v_mov_b32_e32 v255, 0
	s_nop 1
	v_mfma_f32_32x32x16_bf16 v[0:15], v[252:255], v[252:255], 0
	v_mfma_f32_32x32x16_bf16 v[16:31], v[252:255], v[252:255], 0
	v_mfma_f32_32x32x16_bf16 v[32:47], v[252:255], v[252:255], 0
	v_mfma_f32_32x32x16_bf16 v[48:63], v[252:255], v[252:255], 0
	v_mfma_f32_32x32x16_bf16 v[64:79], v[252:255], v[252:255], 0
	v_mfma_f32_32x32x16_bf16 v[80:95], v[252:255], v[252:255], 0
	v_mfma_f32_32x32x16_bf16 v[96:111], v[252:255], v[252:255], 0
	v_mfma_f32_32x32x16_bf16 v[112:127], v[252:255], v[252:255], 0
